# S5 pass-2: counted vmcnt(9) waits instead of vmcnt(0) at the chunk-loop header so the 4-deep XB prefetch ring stays in flight
# speedup vs baseline: 1.0107x; 1.0107x over previous
.LBB0_185:
	s_or_b64 exec, exec, s[2:3]
	s_lshl_b32 s24, s14, 2
	v_lshl_add_u64 v[0:1], v[160:161], 0, s[24:25]
	s_waitcnt vmcnt(0)
	global_load_dwordx4 v[96:99], v[0:1], off
	global_load_dwordx4 v[100:103], v[0:1], off offset:32
	s_lshl_b32 s2, s66, 7
	s_and_b32 s2, s2, 0xffffe000
	v_or3_b32 v120, s2, v197, v155
	v_ashrrev_i32_e32 v121, 31, v120
	v_lshl_add_u64 v[0:1], v[168:169], 0, v[120:121]
	v_lshl_add_u64 v[2:3], v[166:167], 0, v[120:121]
	v_lshl_add_u64 v[4:5], v[164:165], 0, v[120:121]
	v_lshl_add_u64 v[6:7], v[162:163], 0, v[120:121]
	v_cndmask_b32_e64 v1, v1, 0, s[10:11]
	v_cndmask_b32_e64 v0, v0, v154, s[10:11]
	v_cndmask_b32_e64 v3, v3, 0, s[8:9]
	v_cndmask_b32_e64 v2, v2, v154, s[8:9]
	v_cndmask_b32_e64 v5, v5, 0, s[6:7]
	v_cndmask_b32_e64 v4, v4, v154, s[6:7]
	v_cndmask_b32_e64 v7, v7, 0, s[4:5]
	v_cndmask_b32_e64 v6, v6, v154, s[4:5]
	v_lshlrev_b64 v[0:1], 11, v[0:1]
	v_mov_b32_e32 v185, v149
	v_lshlrev_b64 v[2:3], 11, v[2:3]
	v_lshlrev_b64 v[4:5], 11, v[4:5]
	v_lshlrev_b64 v[6:7], 11, v[6:7]
	v_lshl_add_u64 v[0:1], s[84:85], 0, v[0:1]
	v_lshl_add_u64 v[2:3], s[84:85], 0, v[2:3]
	v_lshl_add_u64 v[4:5], s[84:85], 0, v[4:5]
	v_lshl_add_u64 v[6:7], s[84:85], 0, v[6:7]
	v_lshl_add_u64 v[0:1], v[0:1], 0, v[184:185]
	v_lshl_add_u64 v[2:3], v[2:3], 0, v[184:185]
	v_lshl_add_u64 v[4:5], v[4:5], 0, v[184:185]
	v_lshl_add_u64 v[6:7], v[6:7], 0, v[184:185]
	s_lshl_b32 s24, s14, 1
	s_cmp_lt_u32 s66, 64
	s_cselect_b64 s[2:3], -1, 0
	v_lshl_add_u64 v[126:127], v[170:171], 0, s[24:25]
	v_lshl_add_u64 v[184:185], s[84:85], 0, v[184:185]
	s_and_b64 s[50:51], s[2:3], s[12:13]
	s_mov_b32 s24, s28
	s_waitcnt vmcnt(0)
	global_load_dwordx4 v[112:115], v[0:1], off
	global_load_dwordx4 v[116:119], v[2:3], off
	global_load_dwordx4 v[104:107], v[4:5], off
	global_load_dwordx4 v[108:111], v[6:7], off
	v_add_u32_e32 v0, s15, v205
	v_ashrrev_i32_e32 v1, 31, v0
	v_lshl_add_u64 v[122:123], s[42:43], 0, v[0:1]
	v_lshl_add_u64 v[124:125], s[44:45], 0, v[0:1]
	s_waitcnt vmcnt(0)
	s_branch .LBB0_188

.LBB0_188:
	s_waitcnt vmcnt(9)
	v_mfma_f32_32x32x16_bf16 v[16:31], v[108:111], v[132:135], 0
	v_mov_b32_e32 v33, v51
	v_mul_f32_e64 v34, v174, v32
	v_mul_f32_e64 v35, v175, v33
	v_add_u32_e32 v148, v200, v150
	v_sub_f32_e32 v33, v34, v35
	v_mov_b32_e32 v34, v51
	v_mov_b32_e32 v35, v32
	v_pk_mul_f32 v[50:51], v[176:177], v[50:51] op_sel_hi:[1,0]
	v_pk_mul_f32 v[52:53], v[174:175], v[34:35]
	v_pk_fma_f32 v[188:189], v[172:173], v[48:49], v[50:51] neg_lo:[0,0,1] neg_hi:[0,0,1]
	v_pk_fma_f32 v[48:49], v[172:173], v[48:49], v[50:51] op_sel_hi:[1,0,1]
	v_mfma_f32_32x32x16_bf16 v[0:15], v[108:111], v[128:131], 0
	v_add_f32_e32 v186, v33, v16
	v_add_f32_e32 v16, v52, v53
	v_mov_b32_e32 v189, v49
	ds_write_b128 v148, v[108:111] offset:8192
	s_cmp_gt_i32 s24, 0
	s_cselect_b64 s[2:3], -1, 0
	s_or_b64 s[14:15], s[2:3], s[50:51]
	v_mfma_f32_32x32x16_bf16 v[48:63], v[108:111], v[136:139], 0
	s_nop 3
	v_mov_b32_e32 v190, v0
	v_mfma_f32_32x32x16_bf16 v[32:47], v[108:111], v[140:143], 0
	s_nop 5
	v_mov_b32_e32 v191, v48
	v_add_f32_e64 v108, v188, v190
	v_add_f32_e64 v109, v189, v191
	v_mul_f32_e64 v110, v172, v108
	v_mul_f32_e64 v111, v173, v109
	v_sub_f32_e32 v0, v110, v111
	v_pk_mul_f32 v[110:111], v[176:177], v[108:109]
	v_add_f32_e32 v16, v16, v32
	v_add_f32_e32 v0, v1, v0
	v_add_f32_e32 v1, v110, v111
	v_add_f32_e32 v110, v49, v1
	v_pk_mul_f32 v[48:49], v[178:179], v[16:17] op_sel_hi:[1,0]
	v_mov_b32_e32 v32, v17
	v_pk_fma_f32 v[188:189], v[174:175], v[186:187], v[48:49] neg_lo:[0,0,1] neg_hi:[0,0,1]
	v_pk_fma_f32 v[48:49], v[174:175], v[186:187], v[48:49] op_sel_hi:[1,0,1]
	s_nop 0
	v_mov_b32_e32 v189, v49
	v_pk_add_f32 v[32:33], v[32:33], v[188:189]
	s_nop 0
	v_pk_mul_f32 v[48:49], v[174:175], v[32:33]
	s_nop 0
	v_sub_f32_e32 v1, v48, v49
	v_pk_mul_f32 v[48:49], v[178:179], v[32:33]
	v_add_f32_e32 v189, v18, v1
	v_add_f32_e32 v1, v48, v49
	v_pk_mul_f32 v[48:49], v[176:177], v[110:111] op_sel_hi:[1,0]
	v_add_f32_e32 v191, v34, v1
	v_pk_fma_f32 v[192:193], v[172:173], v[0:1], v[48:49] neg_lo:[0,0,1] neg_hi:[0,0,1]
	v_pk_fma_f32 v[48:49], v[172:173], v[0:1], v[48:49] op_sel_hi:[1,0,1]
	v_mul_f32_e32 v213, v174, v189
	v_mov_b32_e32 v193, v49
	v_mov_b32_e32 v48, v2
	v_mov_b32_e32 v49, v50
	v_pk_add_f32 v[192:193], v[48:49], v[192:193]
	v_mul_f32_e32 v215, v175, v191
	v_pk_mul_f32 v[48:49], v[172:173], v[192:193]
	v_mov_b32_e32 v18, v3
	v_mov_b32_e32 v212, v48
	v_mov_b32_e32 v214, v49
	v_pk_add_f32 v[48:49], v[212:213], v[214:215] neg_lo:[0,1] neg_hi:[0,1]
	v_mov_b32_e32 v190, v193
	v_pk_add_f32 v[2:3], v[18:19], v[48:49]
	v_pk_mul_f32 v[18:19], v[180:181], v[190:191]
	v_mov_b32_e32 v188, v192
	v_pk_fma_f32 v[18:19], v[182:183], v[188:189], v[18:19]
	v_mov_b32_e32 v34, v51
	v_pk_add_f32 v[18:19], v[34:35], v[18:19]
	v_mov_b32_e32 v48, v4
	v_pk_mul_f32 v[34:35], v[182:183], v[18:19]
	v_mov_b32_e32 v49, v20
	v_pk_fma_f32 v[34:35], v[180:181], v[2:3], v[34:35] neg_lo:[0,0,1] neg_hi:[0,0,1]
	v_mov_b32_e32 v50, v52
	v_pk_add_f32 v[34:35], v[48:49], v[34:35]
	v_pk_mul_f32 v[48:49], v[180:181], v[18:19]
	v_mov_b32_e32 v51, v36
	v_pk_fma_f32 v[48:49], v[182:183], v[2:3], v[48:49]
	v_mov_b32_e32 v20, v5
	v_pk_add_f32 v[212:213], v[50:51], v[48:49]
	v_mov_b32_e32 v36, v53
	v_pk_mul_f32 v[48:49], v[182:183], v[212:213]
	v_pk_mul_f32 v[50:51], v[180:181], v[212:213]
	v_pk_fma_f32 v[48:49], v[180:181], v[34:35], v[48:49] neg_lo:[0,0,1] neg_hi:[0,0,1]
	v_pk_fma_f32 v[50:51], v[182:183], v[34:35], v[50:51]
	v_pk_add_f32 v[4:5], v[20:21], v[48:49]
	v_pk_add_f32 v[20:21], v[36:37], v[50:51]
	v_mov_b32_e32 v48, v6
	v_pk_mul_f32 v[36:37], v[182:183], v[20:21]
	v_mov_b32_e32 v49, v22
	v_pk_fma_f32 v[36:37], v[180:181], v[4:5], v[36:37] neg_lo:[0,0,1] neg_hi:[0,0,1]
	v_mov_b32_e32 v50, v54
	v_pk_add_f32 v[36:37], v[48:49], v[36:37]
	v_pk_mul_f32 v[48:49], v[180:181], v[20:21]
	v_mov_b32_e32 v51, v38
	v_pk_fma_f32 v[48:49], v[182:183], v[4:5], v[48:49]
	v_mov_b32_e32 v22, v7
	v_pk_add_f32 v[52:53], v[50:51], v[48:49]
	v_mov_b32_e32 v38, v55
	v_pk_mul_f32 v[48:49], v[182:183], v[52:53]
	v_mov_b32_e32 v214, v8
	v_pk_fma_f32 v[48:49], v[180:181], v[36:37], v[48:49] neg_lo:[0,0,1] neg_hi:[0,0,1]
	v_mov_b32_e32 v215, v24
	v_pk_add_f32 v[6:7], v[22:23], v[48:49]
	v_pk_mul_f32 v[22:23], v[180:181], v[52:53]
	v_mov_b32_e32 v48, v56
	v_pk_fma_f32 v[22:23], v[182:183], v[36:37], v[22:23]
	v_mov_b32_e32 v49, v40
	v_pk_add_f32 v[22:23], v[38:39], v[22:23]
	v_mov_b32_e32 v24, v9
	v_pk_mul_f32 v[38:39], v[180:181], v[22:23]
	v_pk_mul_f32 v[54:55], v[182:183], v[22:23]
	v_pk_fma_f32 v[38:39], v[182:183], v[6:7], v[38:39]
	v_pk_fma_f32 v[54:55], v[180:181], v[6:7], v[54:55] neg_lo:[0,0,1] neg_hi:[0,0,1]
	v_pk_add_f32 v[38:39], v[48:49], v[38:39]
	v_pk_add_f32 v[54:55], v[214:215], v[54:55]
	v_pk_mul_f32 v[48:49], v[182:183], v[38:39]
	v_pk_mul_f32 v[50:51], v[180:181], v[38:39]
	v_pk_fma_f32 v[48:49], v[180:181], v[54:55], v[48:49] neg_lo:[0,0,1] neg_hi:[0,0,1]
	v_mov_b32_e32 v40, v57
	v_pk_add_f32 v[8:9], v[24:25], v[48:49]
	v_pk_fma_f32 v[24:25], v[182:183], v[54:55], v[50:51]
	v_mov_b32_e32 v48, v10
	v_pk_add_f32 v[24:25], v[40:41], v[24:25]
	v_mov_b32_e32 v49, v26
	v_pk_mul_f32 v[40:41], v[182:183], v[24:25]
	v_mov_b32_e32 v50, v58
	v_pk_fma_f32 v[40:41], v[180:181], v[8:9], v[40:41] neg_lo:[0,0,1] neg_hi:[0,0,1]
	v_mov_b32_e32 v51, v42
	v_pk_add_f32 v[40:41], v[48:49], v[40:41]
	v_pk_mul_f32 v[48:49], v[180:181], v[24:25]
	v_mov_b32_e32 v26, v11
	v_pk_fma_f32 v[48:49], v[182:183], v[8:9], v[48:49]
	v_mov_b32_e32 v42, v59
	v_pk_add_f32 v[56:57], v[50:51], v[48:49]
	v_mov_b32_e32 v50, v60
	v_pk_mul_f32 v[48:49], v[182:183], v[56:57]
	v_mov_b32_e32 v51, v44
	v_pk_fma_f32 v[48:49], v[180:181], v[40:41], v[48:49] neg_lo:[0,0,1] neg_hi:[0,0,1]
	v_mov_b32_e32 v44, v61
	v_pk_add_f32 v[10:11], v[26:27], v[48:49]
	v_pk_mul_f32 v[26:27], v[180:181], v[56:57]
	v_mov_b32_e32 v48, v12
	v_pk_fma_f32 v[26:27], v[182:183], v[40:41], v[26:27]
	v_mov_b32_e32 v49, v28
	v_pk_add_f32 v[26:27], v[42:43], v[26:27]
	v_mov_b32_e32 v28, v13
	v_pk_mul_f32 v[42:43], v[182:183], v[26:27]
	v_cvt_pk_bf16_f32 v0, v108, v0
	v_pk_fma_f32 v[42:43], v[180:181], v[10:11], v[42:43] neg_lo:[0,0,1] neg_hi:[0,0,1]
	v_cvt_pk_bf16_f32 v1, v192, v2
	v_pk_add_f32 v[42:43], v[48:49], v[42:43]
	v_pk_mul_f32 v[48:49], v[180:181], v[26:27]
	v_cvt_pk_bf16_f32 v2, v186, v32
	v_pk_fma_f32 v[48:49], v[182:183], v[10:11], v[48:49]
	v_cvt_pk_bf16_f32 v3, v189, v3
	v_pk_add_f32 v[58:59], v[50:51], v[48:49]
	v_mov_b32_e32 v50, v62
	v_pk_mul_f32 v[48:49], v[182:183], v[58:59]
	v_mov_b32_e32 v51, v46
	v_pk_fma_f32 v[48:49], v[180:181], v[42:43], v[48:49] neg_lo:[0,0,1] neg_hi:[0,0,1]
	v_mov_b32_e32 v46, v63
	v_pk_add_f32 v[12:13], v[28:29], v[48:49]
	v_pk_mul_f32 v[28:29], v[180:181], v[58:59]
	v_mov_b32_e32 v48, v14
	v_pk_fma_f32 v[28:29], v[182:183], v[42:43], v[28:29]
	v_mov_b32_e32 v49, v30
	v_pk_add_f32 v[28:29], v[44:45], v[28:29]
	v_mov_b32_e32 v30, v15
	v_pk_mul_f32 v[44:45], v[182:183], v[28:29]
	ds_write2st64_b64 v207, v[0:1], v[2:3] offset1:4
	v_pk_fma_f32 v[44:45], v[180:181], v[12:13], v[44:45] neg_lo:[0,0,1] neg_hi:[0,0,1]
	v_cvt_pk_bf16_f32 v0, v35, v5
	v_pk_add_f32 v[44:45], v[48:49], v[44:45]
	v_pk_mul_f32 v[48:49], v[180:181], v[28:29]
	v_cvt_pk_bf16_f32 v1, v37, v7
	v_pk_fma_f32 v[48:49], v[182:183], v[12:13], v[48:49]
	v_pk_mov_b32 v[2:3], v[192:193], v[18:19] op_sel:[1,0]
	v_pk_add_f32 v[60:61], v[50:51], v[48:49]
	v_cvt_pk_bf16_f32 v5, v56, v26
	v_pk_mul_f32 v[14:15], v[180:181], v[60:61]
	v_pk_mul_f32 v[48:49], v[182:183], v[60:61]
	v_pk_fma_f32 v[14:15], v[182:183], v[44:45], v[14:15]
	v_pk_fma_f32 v[48:49], v[180:181], v[44:45], v[48:49] neg_lo:[0,0,1] neg_hi:[0,0,1]
	v_pk_add_f32 v[50:51], v[46:47], v[14:15]
	v_cvt_pk_bf16_f32 v14, v34, v4
	v_cvt_pk_bf16_f32 v15, v36, v6
	v_pk_add_f32 v[48:49], v[30:31], v[48:49]
	v_cvt_pk_bf16_f32 v30, v54, v8
	v_cvt_pk_bf16_f32 v31, v40, v10
	ds_write2st64_b64 v208, v[14:15], v[0:1] offset1:4
	v_cvt_pk_bf16_f32 v0, v55, v9
	v_cvt_pk_bf16_f32 v1, v41, v11
	v_cvt_pk_bf16_f32 v46, v42, v12
	v_cvt_pk_bf16_f32 v47, v44, v48
	ds_write2st64_b64 v209, v[30:31], v[0:1] offset1:4
	v_cvt_pk_bf16_f32 v0, v43, v13
	v_cvt_pk_bf16_f32 v1, v45, v49
	ds_write2st64_b64 v210, v[46:47], v[0:1] offset1:4
	v_cvt_pk_bf16_f32 v0, v109, v110
	v_cvt_pk_bf16_f32 v1, v2, v3
	v_cvt_pk_bf16_f32 v8, v16, v33
	v_cvt_pk_bf16_f32 v9, v191, v19
	v_cvt_pk_bf16_f32 v2, v212, v20
	v_cvt_pk_bf16_f32 v3, v52, v22
	ds_write2st64_b64 v207, v[0:1], v[8:9] offset0:8 offset1:12
	v_cvt_pk_bf16_f32 v0, v213, v21
	v_cvt_pk_bf16_f32 v1, v53, v23
	v_cvt_pk_bf16_f32 v4, v38, v24
	ds_write2st64_b64 v208, v[2:3], v[0:1] offset0:8 offset1:12
	v_cvt_pk_bf16_f32 v0, v39, v25
	v_cvt_pk_bf16_f32 v1, v57, v27
	v_cvt_pk_bf16_f32 v6, v58, v28
	v_cvt_pk_bf16_f32 v7, v60, v50
	ds_write2st64_b64 v209, v[4:5], v[0:1] offset0:8 offset1:12
	v_cvt_pk_bf16_f32 v0, v59, v29
	v_cvt_pk_bf16_f32 v1, v61, v51
	ds_write2st64_b64 v210, v[6:7], v[0:1] offset0:8 offset1:12
	s_waitcnt lgkmcnt(0)
	ds_read_b64_tr_b16 v[0:1], v151 offset:0
	ds_read_b64_tr_b16 v[2:3], v199 offset:0
	ds_read_b64_tr_b16 v[28:29], v151 offset:1024
	ds_read_b64_tr_b16 v[30:31], v199 offset:1024
	ds_read_b64_tr_b16 v[24:25], v151 offset:2048
	ds_read_b64_tr_b16 v[26:27], v199 offset:2048
	ds_read_b64_tr_b16 v[20:21], v151 offset:3072
	ds_read_b64_tr_b16 v[22:23], v199 offset:3072
	ds_read_b64_tr_b16 v[16:17], v151 offset:4096
	ds_read_b64_tr_b16 v[18:19], v199 offset:4096
	ds_read_b64_tr_b16 v[44:45], v151 offset:5120
	ds_read_b64_tr_b16 v[46:47], v199 offset:5120
	ds_read_b64_tr_b16 v[40:41], v151 offset:6144
	ds_read_b64_tr_b16 v[42:43], v199 offset:6144
	ds_read_b64_tr_b16 v[52:53], v151 offset:7168
	ds_read_b64_tr_b16 v[54:55], v199 offset:7168
	s_waitcnt lgkmcnt(0)
	s_nop 0
	v_mfma_f32_32x32x16_bf16 v[0:15], v[68:71], v[0:3], 0
	v_mfma_f32_32x32x16_bf16 v[0:15], v[64:67], v[28:31], v[0:15]
	v_mfma_f32_32x32x16_bf16 v[24:39], v[76:79], v[24:27], 0
	v_mfma_f32_32x32x16_bf16 v[24:39], v[72:75], v[20:23], v[24:39]
	v_mfma_f32_32x32x16_bf16 v[8:23], v[84:87], v[16:19], 0
	v_mfma_f32_32x32x16_bf16 v[8:23], v[80:83], v[44:47], v[8:23]
	v_mfma_f32_32x32x16_bf16 v[32:47], v[92:95], v[40:43], 0
	v_mfma_f32_32x32x16_bf16 v[32:47], v[88:91], v[52:55], v[32:47]
	s_and_saveexec_b64 s[2:3], s[14:15]
	s_cbranch_execz .LBB0_190
	s_nop 7
	v_add_u32_e32 v16, v200, v146
	v_add_u32_e32 v16, 0x2000, v16
	ds_read2_b64 v[16:19], v16 offset1:2
	v_pk_add_f32 v[6:7], v[6:7], v[30:31]
	v_pk_add_f32 v[2:3], v[2:3], v[26:27]
	v_pk_add_f32 v[14:15], v[14:15], v[38:39]
	v_pk_add_f32 v[10:11], v[10:11], v[34:35]
	v_pk_add_f32 v[6:7], v[6:7], v[14:15]
	v_pk_add_f32 v[2:3], v[2:3], v[10:11]
	s_waitcnt lgkmcnt(0)
	v_lshlrev_b32_e32 v10, 16, v19
	v_and_b32_e32 v11, 0xffff0000, v19
	v_pk_fma_f32 v[6:7], v[102:103], v[10:11], v[6:7]
	v_pk_add_f32 v[0:1], v[0:1], v[24:25]
	v_mul_f32_e32 v10, 0x3d372713, v7
	v_mul_f32_e32 v10, v7, v10
	v_mul_f32_e32 v11, 0x3d372713, v6
	v_fma_f32 v10, v7, v10, v7
	v_mul_f32_e32 v11, v6, v11
	v_mul_f32_e32 v10, 0xbfcc422a, v10
	v_fma_f32 v11, v6, v11, v6
	v_mul_f32_e32 v10, 0x3fb8aa3b, v10
	v_mul_f32_e32 v11, 0xbfcc422a, v11
	v_exp_f32_e32 v10, v10
	v_mul_f32_e32 v11, 0x3fb8aa3b, v11
	v_exp_f32_e32 v11, v11
	v_pk_add_f32 v[8:9], v[8:9], v[32:33]
	v_pk_add_f32 v[4:5], v[4:5], v[28:29]
	v_pk_add_f32 v[12:13], v[12:13], v[36:37]
	v_pk_add_f32 v[0:1], v[0:1], v[8:9]
	v_add_f32_e32 v8, 1.0, v10
	v_pk_add_f32 v[4:5], v[4:5], v[12:13]
	v_rcp_f32_e32 v9, v8
	v_add_f32_e32 v8, 1.0, v11
	v_lshlrev_b32_e32 v10, 16, v18
	v_and_b32_e32 v11, 0xffff0000, v18
	v_pk_fma_f32 v[4:5], v[100:101], v[10:11], v[4:5]
	v_and_b32_e32 v13, 0xffff0000, v17
	v_mul_f32_e32 v10, 0x3d372713, v5
	v_mul_f32_e32 v10, v5, v10
	v_mul_f32_e32 v11, 0x3d372713, v4
	v_fma_f32 v10, v5, v10, v5
	v_mul_f32_e32 v11, v4, v11
	v_mul_f32_e32 v10, 0xbfcc422a, v10
	v_fma_f32 v11, v4, v11, v4
	v_mul_f32_e32 v10, 0x3fb8aa3b, v10
	v_mul_f32_e32 v11, 0xbfcc422a, v11
	v_exp_f32_e32 v10, v10
	v_mul_f32_e32 v11, 0x3fb8aa3b, v11
	v_exp_f32_e32 v12, v11
	v_and_b32_e32 v15, 0xffff0000, v16
	v_add_f32_e32 v10, 1.0, v10
	v_rcp_f32_e32 v11, v10
	v_add_f32_e32 v10, 1.0, v12
	v_lshlrev_b32_e32 v12, 16, v17
	v_pk_fma_f32 v[2:3], v[98:99], v[12:13], v[2:3]
	v_rcp_f32_e32 v8, v8
	v_mul_f32_e32 v12, 0x3d372713, v3
	v_mul_f32_e32 v12, v3, v12
	v_mul_f32_e32 v13, 0x3d372713, v2
	v_fma_f32 v12, v3, v12, v3
	v_mul_f32_e32 v13, v2, v13
	v_mul_f32_e32 v12, 0xbfcc422a, v12
	v_fma_f32 v13, v2, v13, v2
	v_mul_f32_e32 v12, 0x3fb8aa3b, v12
	v_mul_f32_e32 v13, 0xbfcc422a, v13
	v_exp_f32_e32 v12, v12
	v_mul_f32_e32 v13, 0x3fb8aa3b, v13
	v_exp_f32_e32 v14, v13
	v_rcp_f32_e32 v10, v10
	v_add_f32_e32 v12, 1.0, v12
	v_rcp_f32_e32 v13, v12
	v_add_f32_e32 v12, 1.0, v14
	v_lshlrev_b32_e32 v14, 16, v16
	v_pk_fma_f32 v[0:1], v[96:97], v[14:15], v[0:1]
	v_rcp_f32_e32 v12, v12
	v_mul_f32_e32 v14, 0x3d372713, v1
	v_mul_f32_e32 v14, v1, v14
	v_mul_f32_e32 v15, 0x3d372713, v0
	v_fma_f32 v14, v1, v14, v1
	v_mul_f32_e32 v15, v0, v15
	v_mul_f32_e32 v14, 0xbfcc422a, v14
	v_fma_f32 v15, v0, v15, v0
	v_mul_f32_e32 v14, 0x3fb8aa3b, v14
	v_mul_f32_e32 v15, 0xbfcc422a, v15
	v_exp_f32_e32 v14, v14
	v_mul_f32_e32 v15, 0x3fb8aa3b, v15
	v_exp_f32_e32 v16, v15
	s_cmp_eq_u32 s24, 0
	v_add_f32_e32 v14, 1.0, v14
	v_rcp_f32_e32 v15, v14
	v_add_f32_e32 v14, 1.0, v16
	v_rcp_f32_e32 v14, v14
	s_cselect_b64 vcc, -1, 0
	v_pk_mul_f32 v[6:7], v[6:7], v[8:9]
	v_cndmask_b32_e64 v9, v123, 0, vcc
	v_cndmask_b32_e32 v8, v122, v154, vcc
	v_pk_mul_f32 v[2:3], v[2:3], v[12:13]
	v_pk_mul_f32 v[0:1], v[0:1], v[14:15]
	v_lshlrev_b64 v[8:9], 11, v[8:9]
	v_pk_mul_f32 v[4:5], v[4:5], v[10:11]
	v_lshl_add_u64 v[8:9], v[126:127], 0, v[8:9]
	v_cvt_pk_bf16_f32 v0, v0, v1
	v_cvt_pk_bf16_f32 v1, v2, v3
	v_cvt_pk_bf16_f32 v2, v4, v5
	v_cvt_pk_bf16_f32 v3, v6, v7
	global_store_dwordx2 v[8:9], v[0:1], off
	global_store_dwordx2 v[8:9], v[2:3], off offset:16
.LBB0_190:
	s_or_b64 exec, exec, s[2:3]
	s_add_i32 s67, s24, 4
	s_min_i32 s2, s67, s23
	s_nop 0
	v_sub_co_u32_e64 v0, vcc, s2, 1
	v_ashrrev_i32_e32 v1, 31, v0
	v_lshl_add_u64 v[0:1], v[0:1], 4, v[120:121]
	v_cndmask_b32_e64 v1, v1, 0, vcc
	v_cndmask_b32_e32 v0, v0, v154, vcc
	v_lshlrev_b64 v[0:1], 11, v[0:1]
	v_lshl_add_u64 v[0:1], v[184:185], 0, v[0:1]
	global_load_dwordx4 v[108:111], v[0:1], off
	s_add_i32 s52, s24, 1
	s_cmp_ge_i32 s52, s22
	s_cbranch_scc1 .LBB0_195
	s_waitcnt vmcnt(9)
	v_mfma_f32_32x32x16_bf16 v[16:31], v[104:107], v[132:135], 0
	v_mov_b32_e32 v32, v49
	v_mov_b32_e32 v33, v51
	v_mul_f32_e64 v32, v174, v32
	v_mul_f32_e64 v33, v175, v33
	ds_write_b128 v148, v[104:107] offset:8192
	v_sub_f32_e32 v32, v32, v33
	v_mov_b32_e32 v33, v49
	s_cmp_gt_i32 s24, -1
	s_nop 3
	v_add_f32_e32 v186, v32, v16
	v_mov_b32_e32 v32, v51
	v_pk_mul_f32 v[50:51], v[176:177], v[50:51] op_sel_hi:[1,0]
	v_pk_mul_f32 v[52:53], v[174:175], v[32:33]
	v_pk_fma_f32 v[188:189], v[172:173], v[48:49], v[50:51] neg_lo:[0,0,1] neg_hi:[0,0,1]
	v_pk_fma_f32 v[48:49], v[172:173], v[48:49], v[50:51] op_sel_hi:[1,0,1]
	v_mfma_f32_32x32x16_bf16 v[0:15], v[104:107], v[128:131], 0
	v_add_f32_e32 v16, v53, v52
	v_mov_b32_e32 v189, v49
	s_cselect_b64 s[2:3], -1, 0
	s_or_b64 s[14:15], s[2:3], s[50:51]
	v_mfma_f32_32x32x16_bf16 v[48:63], v[104:107], v[136:139], 0
	s_nop 6
	v_mov_b32_e32 v190, v0
	v_mfma_f32_32x32x16_bf16 v[32:47], v[104:107], v[140:143], 0
	s_nop 2
	v_mov_b32_e32 v191, v48
	v_add_f32_e64 v104, v188, v190
	v_add_f32_e64 v105, v189, v191
	v_mul_f32_e64 v106, v172, v104
	v_mul_f32_e64 v107, v173, v105
	v_sub_f32_e32 v0, v106, v107
	v_pk_mul_f32 v[106:107], v[176:177], v[104:105]
	s_nop 1
	v_add_f32_e32 v16, v16, v32
	v_add_f32_e32 v0, v1, v0
	v_add_f32_e32 v1, v106, v107
	v_add_f32_e32 v106, v49, v1
	v_pk_mul_f32 v[48:49], v[178:179], v[16:17] op_sel_hi:[1,0]
	v_mov_b32_e32 v32, v17
	v_pk_fma_f32 v[188:189], v[174:175], v[186:187], v[48:49] neg_lo:[0,0,1] neg_hi:[0,0,1]
	v_pk_fma_f32 v[48:49], v[174:175], v[186:187], v[48:49] op_sel_hi:[1,0,1]
	s_nop 0
	v_mov_b32_e32 v189, v49
	v_pk_add_f32 v[32:33], v[32:33], v[188:189]
	s_nop 0
	v_pk_mul_f32 v[48:49], v[174:175], v[32:33]
	s_nop 0
	v_sub_f32_e32 v1, v48, v49
	v_pk_mul_f32 v[48:49], v[178:179], v[32:33]
	v_add_f32_e32 v189, v18, v1
	v_add_f32_e32 v1, v48, v49
	v_pk_mul_f32 v[48:49], v[176:177], v[106:107] op_sel_hi:[1,0]
	v_add_f32_e32 v191, v34, v1
	v_pk_fma_f32 v[192:193], v[172:173], v[0:1], v[48:49] neg_lo:[0,0,1] neg_hi:[0,0,1]
	v_pk_fma_f32 v[48:49], v[172:173], v[0:1], v[48:49] op_sel_hi:[1,0,1]
	v_mul_f32_e32 v213, v174, v189
	v_mov_b32_e32 v193, v49
	v_mov_b32_e32 v48, v2
	v_mov_b32_e32 v49, v50
	v_pk_add_f32 v[192:193], v[48:49], v[192:193]
	v_mul_f32_e32 v215, v175, v191
	v_pk_mul_f32 v[48:49], v[172:173], v[192:193]
	v_mov_b32_e32 v18, v3
	v_mov_b32_e32 v212, v48
	v_mov_b32_e32 v214, v49
	v_pk_add_f32 v[48:49], v[212:213], v[214:215] neg_lo:[0,1] neg_hi:[0,1]
	v_mov_b32_e32 v190, v193
	v_pk_add_f32 v[2:3], v[18:19], v[48:49]
	v_pk_mul_f32 v[18:19], v[180:181], v[190:191]
	v_mov_b32_e32 v188, v192
	v_pk_fma_f32 v[18:19], v[182:183], v[188:189], v[18:19]
	v_mov_b32_e32 v34, v51
	v_pk_add_f32 v[18:19], v[34:35], v[18:19]
	v_mov_b32_e32 v48, v4
	v_pk_mul_f32 v[34:35], v[182:183], v[18:19]
	v_mov_b32_e32 v49, v20
	v_pk_fma_f32 v[34:35], v[180:181], v[2:3], v[34:35] neg_lo:[0,0,1] neg_hi:[0,0,1]
	v_mov_b32_e32 v50, v52
	v_pk_add_f32 v[34:35], v[48:49], v[34:35]
	v_pk_mul_f32 v[48:49], v[180:181], v[18:19]
	v_mov_b32_e32 v51, v36
	v_pk_fma_f32 v[48:49], v[182:183], v[2:3], v[48:49]
	v_mov_b32_e32 v20, v5
	v_pk_add_f32 v[212:213], v[50:51], v[48:49]
	v_mov_b32_e32 v36, v53
	v_pk_mul_f32 v[48:49], v[182:183], v[212:213]
	v_pk_mul_f32 v[50:51], v[180:181], v[212:213]
	v_pk_fma_f32 v[48:49], v[180:181], v[34:35], v[48:49] neg_lo:[0,0,1] neg_hi:[0,0,1]
	v_pk_fma_f32 v[50:51], v[182:183], v[34:35], v[50:51]
	v_pk_add_f32 v[4:5], v[20:21], v[48:49]
	v_pk_add_f32 v[20:21], v[36:37], v[50:51]
	v_mov_b32_e32 v48, v6
	v_pk_mul_f32 v[36:37], v[182:183], v[20:21]
	v_mov_b32_e32 v49, v22
	v_pk_fma_f32 v[36:37], v[180:181], v[4:5], v[36:37] neg_lo:[0,0,1] neg_hi:[0,0,1]
	v_mov_b32_e32 v50, v54
	v_pk_add_f32 v[36:37], v[48:49], v[36:37]
	v_pk_mul_f32 v[48:49], v[180:181], v[20:21]
	v_mov_b32_e32 v51, v38
	v_pk_fma_f32 v[48:49], v[182:183], v[4:5], v[48:49]
	v_mov_b32_e32 v22, v7
	v_pk_add_f32 v[52:53], v[50:51], v[48:49]
	v_mov_b32_e32 v38, v55
	v_pk_mul_f32 v[48:49], v[182:183], v[52:53]
	v_mov_b32_e32 v214, v8
	v_pk_fma_f32 v[48:49], v[180:181], v[36:37], v[48:49] neg_lo:[0,0,1] neg_hi:[0,0,1]
	v_mov_b32_e32 v215, v24
	v_pk_add_f32 v[6:7], v[22:23], v[48:49]
	v_pk_mul_f32 v[22:23], v[180:181], v[52:53]
	v_mov_b32_e32 v48, v56
	v_pk_fma_f32 v[22:23], v[182:183], v[36:37], v[22:23]
	v_mov_b32_e32 v49, v40
	v_pk_add_f32 v[22:23], v[38:39], v[22:23]
	v_mov_b32_e32 v24, v9
	v_pk_mul_f32 v[38:39], v[180:181], v[22:23]
	v_pk_mul_f32 v[54:55], v[182:183], v[22:23]
	v_pk_fma_f32 v[38:39], v[182:183], v[6:7], v[38:39]
	v_pk_fma_f32 v[54:55], v[180:181], v[6:7], v[54:55] neg_lo:[0,0,1] neg_hi:[0,0,1]
	v_pk_add_f32 v[38:39], v[48:49], v[38:39]
	v_pk_add_f32 v[54:55], v[214:215], v[54:55]
	v_pk_mul_f32 v[48:49], v[182:183], v[38:39]
	v_pk_mul_f32 v[50:51], v[180:181], v[38:39]
	v_pk_fma_f32 v[48:49], v[180:181], v[54:55], v[48:49] neg_lo:[0,0,1] neg_hi:[0,0,1]
	v_mov_b32_e32 v40, v57
	v_pk_add_f32 v[8:9], v[24:25], v[48:49]
	v_pk_fma_f32 v[24:25], v[182:183], v[54:55], v[50:51]
	v_mov_b32_e32 v48, v10
	v_pk_add_f32 v[24:25], v[40:41], v[24:25]
	v_mov_b32_e32 v49, v26
	v_pk_mul_f32 v[40:41], v[182:183], v[24:25]
	v_mov_b32_e32 v50, v58
	v_pk_fma_f32 v[40:41], v[180:181], v[8:9], v[40:41] neg_lo:[0,0,1] neg_hi:[0,0,1]
	v_mov_b32_e32 v51, v42
	v_pk_add_f32 v[40:41], v[48:49], v[40:41]
	v_pk_mul_f32 v[48:49], v[180:181], v[24:25]
	v_mov_b32_e32 v26, v11
	v_pk_fma_f32 v[48:49], v[182:183], v[8:9], v[48:49]
	v_mov_b32_e32 v42, v59
	v_pk_add_f32 v[56:57], v[50:51], v[48:49]
	v_mov_b32_e32 v50, v60
	v_pk_mul_f32 v[48:49], v[182:183], v[56:57]
	v_mov_b32_e32 v51, v44
	v_pk_fma_f32 v[48:49], v[180:181], v[40:41], v[48:49] neg_lo:[0,0,1] neg_hi:[0,0,1]
	v_mov_b32_e32 v44, v61
	v_pk_add_f32 v[10:11], v[26:27], v[48:49]
	v_pk_mul_f32 v[26:27], v[180:181], v[56:57]
	v_mov_b32_e32 v48, v12
	v_pk_fma_f32 v[26:27], v[182:183], v[40:41], v[26:27]
	v_mov_b32_e32 v49, v28
	v_pk_add_f32 v[26:27], v[42:43], v[26:27]
	v_mov_b32_e32 v28, v13
	v_pk_mul_f32 v[42:43], v[182:183], v[26:27]
	v_cvt_pk_bf16_f32 v0, v104, v0
	v_pk_fma_f32 v[42:43], v[180:181], v[10:11], v[42:43] neg_lo:[0,0,1] neg_hi:[0,0,1]
	v_cvt_pk_bf16_f32 v1, v192, v2
	v_pk_add_f32 v[42:43], v[48:49], v[42:43]
	v_pk_mul_f32 v[48:49], v[180:181], v[26:27]
	v_cvt_pk_bf16_f32 v2, v186, v32
	v_pk_fma_f32 v[48:49], v[182:183], v[10:11], v[48:49]
	v_cvt_pk_bf16_f32 v3, v189, v3
	v_pk_add_f32 v[58:59], v[50:51], v[48:49]
	v_mov_b32_e32 v50, v62
	v_pk_mul_f32 v[48:49], v[182:183], v[58:59]
	v_mov_b32_e32 v51, v46
	v_pk_fma_f32 v[48:49], v[180:181], v[42:43], v[48:49] neg_lo:[0,0,1] neg_hi:[0,0,1]
	v_mov_b32_e32 v46, v63
	v_pk_add_f32 v[12:13], v[28:29], v[48:49]
	v_pk_mul_f32 v[28:29], v[180:181], v[58:59]
	v_mov_b32_e32 v48, v14
	v_pk_fma_f32 v[28:29], v[182:183], v[42:43], v[28:29]
	v_mov_b32_e32 v49, v30
	v_pk_add_f32 v[28:29], v[44:45], v[28:29]
	v_mov_b32_e32 v30, v15
	v_pk_mul_f32 v[44:45], v[182:183], v[28:29]
	ds_write2st64_b64 v207, v[0:1], v[2:3] offset1:4
	v_pk_fma_f32 v[44:45], v[180:181], v[12:13], v[44:45] neg_lo:[0,0,1] neg_hi:[0,0,1]
	v_cvt_pk_bf16_f32 v0, v35, v5
	v_pk_add_f32 v[44:45], v[48:49], v[44:45]
	v_pk_mul_f32 v[48:49], v[180:181], v[28:29]
	v_cvt_pk_bf16_f32 v1, v37, v7
	v_pk_fma_f32 v[48:49], v[182:183], v[12:13], v[48:49]
	v_pk_mov_b32 v[2:3], v[192:193], v[18:19] op_sel:[1,0]
	v_pk_add_f32 v[60:61], v[50:51], v[48:49]
	v_cvt_pk_bf16_f32 v5, v56, v26
	v_pk_mul_f32 v[14:15], v[180:181], v[60:61]
	v_pk_mul_f32 v[48:49], v[182:183], v[60:61]
	v_pk_fma_f32 v[14:15], v[182:183], v[44:45], v[14:15]
	v_pk_fma_f32 v[48:49], v[180:181], v[44:45], v[48:49] neg_lo:[0,0,1] neg_hi:[0,0,1]
	v_pk_add_f32 v[50:51], v[46:47], v[14:15]
	v_cvt_pk_bf16_f32 v14, v34, v4
	v_cvt_pk_bf16_f32 v15, v36, v6
	v_pk_add_f32 v[48:49], v[30:31], v[48:49]
	v_cvt_pk_bf16_f32 v30, v54, v8
	v_cvt_pk_bf16_f32 v31, v40, v10
	ds_write2st64_b64 v208, v[14:15], v[0:1] offset1:4
	v_cvt_pk_bf16_f32 v0, v55, v9
	v_cvt_pk_bf16_f32 v1, v41, v11
	v_cvt_pk_bf16_f32 v46, v42, v12
	v_cvt_pk_bf16_f32 v47, v44, v48
	ds_write2st64_b64 v209, v[30:31], v[0:1] offset1:4
	v_cvt_pk_bf16_f32 v0, v43, v13
	v_cvt_pk_bf16_f32 v1, v45, v49
	ds_write2st64_b64 v210, v[46:47], v[0:1] offset1:4
	v_cvt_pk_bf16_f32 v0, v105, v106
	v_cvt_pk_bf16_f32 v1, v2, v3
	v_cvt_pk_bf16_f32 v8, v16, v33
	v_cvt_pk_bf16_f32 v9, v191, v19
	v_cvt_pk_bf16_f32 v2, v212, v20
	v_cvt_pk_bf16_f32 v3, v52, v22
	ds_write2st64_b64 v207, v[0:1], v[8:9] offset0:8 offset1:12
	v_cvt_pk_bf16_f32 v0, v213, v21
	v_cvt_pk_bf16_f32 v1, v53, v23
	v_cvt_pk_bf16_f32 v4, v38, v24
	ds_write2st64_b64 v208, v[2:3], v[0:1] offset0:8 offset1:12
	v_cvt_pk_bf16_f32 v0, v39, v25
	v_cvt_pk_bf16_f32 v1, v57, v27
	v_cvt_pk_bf16_f32 v6, v58, v28
	v_cvt_pk_bf16_f32 v7, v60, v50
	ds_write2st64_b64 v209, v[4:5], v[0:1] offset0:8 offset1:12
	v_cvt_pk_bf16_f32 v0, v59, v29
	v_cvt_pk_bf16_f32 v1, v61, v51
	ds_write2st64_b64 v210, v[6:7], v[0:1] offset0:8 offset1:12
	s_waitcnt lgkmcnt(0)
	ds_read_b64_tr_b16 v[0:1], v151 offset:0
	ds_read_b64_tr_b16 v[2:3], v199 offset:0
	ds_read_b64_tr_b16 v[28:29], v151 offset:1024
	ds_read_b64_tr_b16 v[30:31], v199 offset:1024
	ds_read_b64_tr_b16 v[24:25], v151 offset:2048
	ds_read_b64_tr_b16 v[26:27], v199 offset:2048
	ds_read_b64_tr_b16 v[20:21], v151 offset:3072
	ds_read_b64_tr_b16 v[22:23], v199 offset:3072
	ds_read_b64_tr_b16 v[16:17], v151 offset:4096
	ds_read_b64_tr_b16 v[18:19], v199 offset:4096
	ds_read_b64_tr_b16 v[44:45], v151 offset:5120
	ds_read_b64_tr_b16 v[46:47], v199 offset:5120
	ds_read_b64_tr_b16 v[40:41], v151 offset:6144
	ds_read_b64_tr_b16 v[42:43], v199 offset:6144
	ds_read_b64_tr_b16 v[52:53], v151 offset:7168
	ds_read_b64_tr_b16 v[54:55], v199 offset:7168
	s_waitcnt lgkmcnt(0)
	s_nop 0
	v_mfma_f32_32x32x16_bf16 v[0:15], v[68:71], v[0:3], 0
	v_mfma_f32_32x32x16_bf16 v[0:15], v[64:67], v[28:31], v[0:15]
	v_mfma_f32_32x32x16_bf16 v[24:39], v[76:79], v[24:27], 0
	v_mfma_f32_32x32x16_bf16 v[24:39], v[72:75], v[20:23], v[24:39]
	v_mfma_f32_32x32x16_bf16 v[8:23], v[84:87], v[16:19], 0
	v_mfma_f32_32x32x16_bf16 v[8:23], v[80:83], v[44:47], v[8:23]
	v_mfma_f32_32x32x16_bf16 v[32:47], v[92:95], v[40:43], 0
	v_mfma_f32_32x32x16_bf16 v[32:47], v[88:91], v[52:55], v[32:47]
	s_and_saveexec_b64 s[2:3], s[14:15]
	s_cbranch_execz .LBB0_193
	s_nop 7
	v_add_u32_e32 v16, v200, v146
	v_add_u32_e32 v16, 0x2000, v16
	ds_read2_b64 v[16:19], v16 offset1:2
	v_pk_add_f32 v[6:7], v[6:7], v[30:31]
	v_pk_add_f32 v[2:3], v[2:3], v[26:27]
	v_pk_add_f32 v[14:15], v[14:15], v[38:39]
	v_pk_add_f32 v[10:11], v[10:11], v[34:35]
	v_pk_add_f32 v[6:7], v[6:7], v[14:15]
	v_pk_add_f32 v[2:3], v[2:3], v[10:11]
	s_waitcnt lgkmcnt(0)
	v_lshlrev_b32_e32 v10, 16, v19
	v_and_b32_e32 v11, 0xffff0000, v19
	v_pk_fma_f32 v[6:7], v[102:103], v[10:11], v[6:7]
	v_pk_add_f32 v[0:1], v[0:1], v[24:25]
	v_mul_f32_e32 v10, 0x3d372713, v7
	v_mul_f32_e32 v10, v7, v10
	v_mul_f32_e32 v11, 0x3d372713, v6
	v_fma_f32 v10, v7, v10, v7
	v_mul_f32_e32 v11, v6, v11
	v_mul_f32_e32 v10, 0xbfcc422a, v10
	v_fma_f32 v11, v6, v11, v6
	v_mul_f32_e32 v10, 0x3fb8aa3b, v10
	v_mul_f32_e32 v11, 0xbfcc422a, v11
	v_exp_f32_e32 v10, v10
	v_mul_f32_e32 v11, 0x3fb8aa3b, v11
	v_exp_f32_e32 v11, v11
	v_pk_add_f32 v[8:9], v[8:9], v[32:33]
	v_pk_add_f32 v[4:5], v[4:5], v[28:29]
	v_pk_add_f32 v[12:13], v[12:13], v[36:37]
	v_pk_add_f32 v[0:1], v[0:1], v[8:9]
	v_add_f32_e32 v8, 1.0, v10
	v_pk_add_f32 v[4:5], v[4:5], v[12:13]
	v_rcp_f32_e32 v9, v8
	v_add_f32_e32 v8, 1.0, v11
	v_lshlrev_b32_e32 v10, 16, v18
	v_and_b32_e32 v11, 0xffff0000, v18
	v_pk_fma_f32 v[4:5], v[100:101], v[10:11], v[4:5]
	v_and_b32_e32 v13, 0xffff0000, v17
	v_mul_f32_e32 v10, 0x3d372713, v5
	v_mul_f32_e32 v10, v5, v10
	v_mul_f32_e32 v11, 0x3d372713, v4
	v_fma_f32 v10, v5, v10, v5
	v_mul_f32_e32 v11, v4, v11
	v_mul_f32_e32 v10, 0xbfcc422a, v10
	v_fma_f32 v11, v4, v11, v4
	v_mul_f32_e32 v10, 0x3fb8aa3b, v10
	v_mul_f32_e32 v11, 0xbfcc422a, v11
	v_exp_f32_e32 v10, v10
	v_mul_f32_e32 v11, 0x3fb8aa3b, v11
	v_exp_f32_e32 v12, v11
	v_and_b32_e32 v15, 0xffff0000, v16
	v_add_f32_e32 v10, 1.0, v10
	v_rcp_f32_e32 v11, v10
	v_add_f32_e32 v10, 1.0, v12
	v_lshlrev_b32_e32 v12, 16, v17
	v_pk_fma_f32 v[2:3], v[98:99], v[12:13], v[2:3]
	v_rcp_f32_e32 v8, v8
	v_mul_f32_e32 v12, 0x3d372713, v3
	v_mul_f32_e32 v12, v3, v12
	v_mul_f32_e32 v13, 0x3d372713, v2
	v_fma_f32 v12, v3, v12, v3
	v_mul_f32_e32 v13, v2, v13
	v_mul_f32_e32 v12, 0xbfcc422a, v12
	v_fma_f32 v13, v2, v13, v2
	v_mul_f32_e32 v12, 0x3fb8aa3b, v12
	v_mul_f32_e32 v13, 0xbfcc422a, v13
	v_exp_f32_e32 v12, v12
	v_mul_f32_e32 v13, 0x3fb8aa3b, v13
	v_exp_f32_e32 v14, v13
	v_rcp_f32_e32 v10, v10
	v_add_f32_e32 v12, 1.0, v12
	v_rcp_f32_e32 v13, v12
	v_add_f32_e32 v12, 1.0, v14
	v_lshlrev_b32_e32 v14, 16, v16
	v_pk_fma_f32 v[0:1], v[96:97], v[14:15], v[0:1]
	v_rcp_f32_e32 v12, v12
	v_mul_f32_e32 v14, 0x3d372713, v1
	v_mul_f32_e32 v14, v1, v14
	v_mul_f32_e32 v15, 0x3d372713, v0
	v_fma_f32 v14, v1, v14, v1
	v_mul_f32_e32 v15, v0, v15
	v_mul_f32_e32 v14, 0xbfcc422a, v14
	v_fma_f32 v15, v0, v15, v0
	v_mul_f32_e32 v14, 0x3fb8aa3b, v14
	v_mul_f32_e32 v15, 0xbfcc422a, v15
	v_exp_f32_e32 v14, v14
	v_mul_f32_e32 v15, 0x3fb8aa3b, v15
	v_exp_f32_e32 v16, v15
	s_cmp_eq_u32 s24, -1
	v_add_f32_e32 v14, 1.0, v14
	v_rcp_f32_e32 v15, v14
	v_add_f32_e32 v14, 1.0, v16
	v_rcp_f32_e32 v14, v14
	s_cselect_b64 vcc, -1, 0
	v_pk_mul_f32 v[6:7], v[6:7], v[8:9]
	v_cndmask_b32_e64 v9, v125, 0, vcc
	v_cndmask_b32_e32 v8, v124, v154, vcc
	v_pk_mul_f32 v[2:3], v[2:3], v[12:13]
	v_pk_mul_f32 v[0:1], v[0:1], v[14:15]
	v_lshlrev_b64 v[8:9], 11, v[8:9]
	v_pk_mul_f32 v[4:5], v[4:5], v[10:11]
	v_lshl_add_u64 v[8:9], v[126:127], 0, v[8:9]
	v_cvt_pk_bf16_f32 v0, v0, v1
	v_cvt_pk_bf16_f32 v1, v2, v3
	v_cvt_pk_bf16_f32 v2, v4, v5
	v_cvt_pk_bf16_f32 v3, v6, v7
	global_store_dwordx2 v[8:9], v[0:1], off
	global_store_dwordx2 v[8:9], v[2:3], off offset:16

.LBB0_196:
	s_waitcnt vmcnt(9)
	v_mfma_f32_32x32x16_bf16 v[16:31], v[116:119], v[132:135], 0
	v_mov_b32_e32 v32, v49
	v_mov_b32_e32 v33, v51
	v_mul_f32_e64 v32, v174, v32
	v_mul_f32_e64 v33, v175, v33
	ds_write_b128 v148, v[116:119] offset:8192
	v_sub_f32_e32 v32, v32, v33
	v_mov_b32_e32 v33, v49
	s_cmp_gt_i32 s24, -2
	s_nop 3
	v_add_f32_e32 v186, v32, v16
	v_mov_b32_e32 v32, v51
	v_pk_mul_f32 v[50:51], v[176:177], v[50:51] op_sel_hi:[1,0]
	v_pk_mul_f32 v[52:53], v[174:175], v[32:33]
	v_pk_fma_f32 v[188:189], v[172:173], v[48:49], v[50:51] neg_lo:[0,0,1] neg_hi:[0,0,1]
	v_pk_fma_f32 v[48:49], v[172:173], v[48:49], v[50:51] op_sel_hi:[1,0,1]
	v_mfma_f32_32x32x16_bf16 v[0:15], v[116:119], v[128:131], 0
	v_add_f32_e32 v16, v52, v53
	v_mov_b32_e32 v189, v49
	s_cselect_b64 s[2:3], -1, 0
	s_or_b64 s[68:69], s[2:3], s[50:51]
	v_mfma_f32_32x32x16_bf16 v[48:63], v[116:119], v[136:139], 0
	s_nop 6
	v_mov_b32_e32 v190, v0
	v_mfma_f32_32x32x16_bf16 v[32:47], v[116:119], v[140:143], 0
	s_nop 2
	v_mov_b32_e32 v191, v48
	v_add_f32_e64 v116, v188, v190
	v_add_f32_e64 v117, v189, v191
	v_mul_f32_e64 v118, v172, v116
	v_mul_f32_e64 v119, v173, v117
	v_sub_f32_e32 v0, v118, v119
	v_pk_mul_f32 v[118:119], v[176:177], v[116:117]
	s_nop 1
	v_add_f32_e32 v16, v16, v32
	v_add_f32_e32 v0, v1, v0
	v_add_f32_e32 v1, v118, v119
	v_add_f32_e32 v118, v49, v1
	v_pk_mul_f32 v[48:49], v[178:179], v[16:17] op_sel_hi:[1,0]
	v_mov_b32_e32 v32, v17
	v_pk_fma_f32 v[188:189], v[174:175], v[186:187], v[48:49] neg_lo:[0,0,1] neg_hi:[0,0,1]
	v_pk_fma_f32 v[48:49], v[174:175], v[186:187], v[48:49] op_sel_hi:[1,0,1]
	s_nop 0
	v_mov_b32_e32 v189, v49
	v_pk_add_f32 v[32:33], v[32:33], v[188:189]
	s_nop 0
	v_pk_mul_f32 v[48:49], v[174:175], v[32:33]
	s_nop 0
	v_sub_f32_e32 v1, v48, v49
	v_pk_mul_f32 v[48:49], v[178:179], v[32:33]
	v_add_f32_e32 v189, v18, v1
	v_add_f32_e32 v1, v48, v49
	v_pk_mul_f32 v[48:49], v[176:177], v[118:119] op_sel_hi:[1,0]
	v_add_f32_e32 v191, v34, v1
	v_pk_fma_f32 v[192:193], v[172:173], v[0:1], v[48:49] neg_lo:[0,0,1] neg_hi:[0,0,1]
	v_pk_fma_f32 v[48:49], v[172:173], v[0:1], v[48:49] op_sel_hi:[1,0,1]
	v_mul_f32_e32 v213, v174, v189
	v_mov_b32_e32 v193, v49
	v_mov_b32_e32 v48, v2
	v_mov_b32_e32 v49, v50
	v_pk_add_f32 v[192:193], v[48:49], v[192:193]
	v_mul_f32_e32 v215, v175, v191
	v_pk_mul_f32 v[48:49], v[172:173], v[192:193]
	v_mov_b32_e32 v18, v3
	v_mov_b32_e32 v212, v48
	v_mov_b32_e32 v214, v49
	v_pk_add_f32 v[48:49], v[212:213], v[214:215] neg_lo:[0,1] neg_hi:[0,1]
	v_mov_b32_e32 v190, v193
	v_pk_add_f32 v[2:3], v[18:19], v[48:49]
	v_pk_mul_f32 v[18:19], v[180:181], v[190:191]
	v_mov_b32_e32 v188, v192
	v_pk_fma_f32 v[18:19], v[182:183], v[188:189], v[18:19]
	v_mov_b32_e32 v34, v51
	v_pk_add_f32 v[18:19], v[34:35], v[18:19]
	v_mov_b32_e32 v48, v52
	v_pk_mul_f32 v[34:35], v[180:181], v[18:19]
	v_mov_b32_e32 v49, v36
	v_pk_fma_f32 v[34:35], v[182:183], v[2:3], v[34:35]
	v_pk_mul_f32 v[212:213], v[182:183], v[18:19]
	v_pk_add_f32 v[34:35], v[48:49], v[34:35]
	v_pk_fma_f32 v[212:213], v[180:181], v[2:3], v[212:213] neg_lo:[0,0,1] neg_hi:[0,0,1]
	v_mov_b32_e32 v214, v4
	v_mov_b32_e32 v215, v20
	v_pk_mul_f32 v[48:49], v[182:183], v[34:35]
	v_pk_add_f32 v[212:213], v[214:215], v[212:213]
	v_pk_mul_f32 v[50:51], v[180:181], v[34:35]
	v_pk_fma_f32 v[48:49], v[180:181], v[212:213], v[48:49] neg_lo:[0,0,1] neg_hi:[0,0,1]
	v_mov_b32_e32 v20, v5
	v_pk_add_f32 v[4:5], v[20:21], v[48:49]
	v_pk_fma_f32 v[20:21], v[182:183], v[212:213], v[50:51]
	v_mov_b32_e32 v36, v53
	v_pk_add_f32 v[20:21], v[36:37], v[20:21]
	v_mov_b32_e32 v48, v6
	v_pk_mul_f32 v[36:37], v[182:183], v[20:21]
	v_mov_b32_e32 v49, v22
	v_pk_fma_f32 v[36:37], v[180:181], v[4:5], v[36:37] neg_lo:[0,0,1] neg_hi:[0,0,1]
	v_mov_b32_e32 v50, v54
	v_pk_add_f32 v[36:37], v[48:49], v[36:37]
	v_pk_mul_f32 v[48:49], v[180:181], v[20:21]
	v_mov_b32_e32 v51, v38
	v_pk_fma_f32 v[48:49], v[182:183], v[4:5], v[48:49]
	v_mov_b32_e32 v22, v7
	v_pk_add_f32 v[52:53], v[50:51], v[48:49]
	v_mov_b32_e32 v38, v55
	v_pk_mul_f32 v[48:49], v[182:183], v[52:53]
	v_mov_b32_e32 v50, v56
	v_pk_fma_f32 v[48:49], v[180:181], v[36:37], v[48:49] neg_lo:[0,0,1] neg_hi:[0,0,1]
	v_mov_b32_e32 v51, v40
	v_pk_add_f32 v[6:7], v[22:23], v[48:49]
	v_pk_mul_f32 v[22:23], v[180:181], v[52:53]
	v_mov_b32_e32 v48, v8
	v_pk_fma_f32 v[22:23], v[182:183], v[36:37], v[22:23]
	v_mov_b32_e32 v49, v24
	v_pk_add_f32 v[22:23], v[38:39], v[22:23]
	v_mov_b32_e32 v24, v9
	v_pk_mul_f32 v[38:39], v[182:183], v[22:23]
	v_mov_b32_e32 v40, v57
	v_pk_fma_f32 v[38:39], v[180:181], v[6:7], v[38:39] neg_lo:[0,0,1] neg_hi:[0,0,1]
	v_cvt_pk_bf16_f32 v0, v116, v0
	v_pk_add_f32 v[38:39], v[48:49], v[38:39]
	v_pk_mul_f32 v[48:49], v[180:181], v[22:23]
	v_cvt_pk_bf16_f32 v1, v192, v2
	v_pk_fma_f32 v[48:49], v[182:183], v[6:7], v[48:49]
	v_cvt_pk_bf16_f32 v2, v186, v32
	v_pk_add_f32 v[54:55], v[50:51], v[48:49]
	v_mov_b32_e32 v50, v58
	v_pk_mul_f32 v[48:49], v[182:183], v[54:55]
	v_mov_b32_e32 v51, v42
	v_pk_fma_f32 v[48:49], v[180:181], v[38:39], v[48:49] neg_lo:[0,0,1] neg_hi:[0,0,1]
	v_mov_b32_e32 v42, v59
	v_pk_add_f32 v[8:9], v[24:25], v[48:49]
	v_pk_mul_f32 v[24:25], v[180:181], v[54:55]
	v_mov_b32_e32 v48, v10
	v_pk_fma_f32 v[24:25], v[182:183], v[38:39], v[24:25]
	v_mov_b32_e32 v49, v26
	v_pk_add_f32 v[24:25], v[40:41], v[24:25]
	v_mov_b32_e32 v26, v11
	v_pk_mul_f32 v[40:41], v[182:183], v[24:25]
	v_cvt_pk_bf16_f32 v3, v189, v3
	v_pk_fma_f32 v[40:41], v[180:181], v[8:9], v[40:41] neg_lo:[0,0,1] neg_hi:[0,0,1]
	ds_write2st64_b64 v207, v[0:1], v[2:3] offset1:4
	v_pk_add_f32 v[40:41], v[48:49], v[40:41]
	v_pk_mul_f32 v[48:49], v[180:181], v[24:25]
	v_cvt_pk_bf16_f32 v0, v213, v5
	v_pk_fma_f32 v[48:49], v[182:183], v[8:9], v[48:49]
	v_cvt_pk_bf16_f32 v1, v37, v7
	v_pk_add_f32 v[56:57], v[50:51], v[48:49]
	v_mov_b32_e32 v50, v12
	v_pk_mul_f32 v[48:49], v[182:183], v[56:57]
	v_mov_b32_e32 v51, v28
	v_pk_fma_f32 v[48:49], v[180:181], v[40:41], v[48:49] neg_lo:[0,0,1] neg_hi:[0,0,1]
	v_mov_b32_e32 v28, v13
	v_pk_add_f32 v[10:11], v[26:27], v[48:49]
	v_pk_mul_f32 v[26:27], v[180:181], v[56:57]
	v_pk_mov_b32 v[2:3], v[192:193], v[18:19] op_sel:[1,0]
	v_pk_fma_f32 v[26:27], v[182:183], v[40:41], v[26:27]
	s_nop 0
	v_pk_add_f32 v[26:27], v[42:43], v[26:27]
	s_nop 0
	v_pk_mul_f32 v[42:43], v[182:183], v[26:27]
	v_pk_mul_f32 v[48:49], v[180:181], v[26:27]
	v_pk_fma_f32 v[42:43], v[180:181], v[10:11], v[42:43] neg_lo:[0,0,1] neg_hi:[0,0,1]
	v_pk_fma_f32 v[48:49], v[182:183], v[10:11], v[48:49]
	v_pk_add_f32 v[42:43], v[50:51], v[42:43]
	v_mov_b32_e32 v50, v60
	v_mov_b32_e32 v51, v44
	v_pk_add_f32 v[58:59], v[50:51], v[48:49]
	v_mov_b32_e32 v44, v61
	v_pk_mul_f32 v[48:49], v[182:183], v[58:59]
	v_mov_b32_e32 v50, v62
	v_pk_fma_f32 v[48:49], v[180:181], v[42:43], v[48:49] neg_lo:[0,0,1] neg_hi:[0,0,1]
	v_mov_b32_e32 v51, v46
	v_pk_add_f32 v[12:13], v[28:29], v[48:49]
	v_pk_mul_f32 v[28:29], v[180:181], v[58:59]
	v_mov_b32_e32 v48, v14
	v_pk_fma_f32 v[28:29], v[182:183], v[42:43], v[28:29]
	v_mov_b32_e32 v49, v30
	v_pk_add_f32 v[28:29], v[44:45], v[28:29]
	v_mov_b32_e32 v30, v15
	v_pk_mul_f32 v[44:45], v[182:183], v[28:29]
	v_mov_b32_e32 v46, v63
	v_pk_fma_f32 v[44:45], v[180:181], v[12:13], v[44:45] neg_lo:[0,0,1] neg_hi:[0,0,1]
	v_cvt_pk_bf16_f32 v5, v56, v26
	v_pk_add_f32 v[44:45], v[48:49], v[44:45]
	v_pk_mul_f32 v[48:49], v[180:181], v[28:29]
	s_nop 0
	v_pk_fma_f32 v[48:49], v[182:183], v[12:13], v[48:49]
	s_nop 0
	v_pk_add_f32 v[60:61], v[50:51], v[48:49]
	s_nop 0
	v_pk_mul_f32 v[14:15], v[180:181], v[60:61]
	v_pk_mul_f32 v[48:49], v[182:183], v[60:61]
	v_pk_fma_f32 v[14:15], v[182:183], v[44:45], v[14:15]
	v_pk_fma_f32 v[48:49], v[180:181], v[44:45], v[48:49] neg_lo:[0,0,1] neg_hi:[0,0,1]
	v_pk_add_f32 v[50:51], v[46:47], v[14:15]
	v_cvt_pk_bf16_f32 v14, v212, v4
	v_cvt_pk_bf16_f32 v15, v36, v6
	v_pk_add_f32 v[48:49], v[30:31], v[48:49]
	v_cvt_pk_bf16_f32 v30, v38, v8
	v_cvt_pk_bf16_f32 v31, v40, v10
	ds_write2st64_b64 v208, v[14:15], v[0:1] offset1:4
	v_cvt_pk_bf16_f32 v0, v39, v9
	v_cvt_pk_bf16_f32 v1, v41, v11
	v_cvt_pk_bf16_f32 v46, v42, v12
	v_cvt_pk_bf16_f32 v47, v44, v48
	ds_write2st64_b64 v209, v[30:31], v[0:1] offset1:4
	v_cvt_pk_bf16_f32 v0, v43, v13
	v_cvt_pk_bf16_f32 v1, v45, v49
	ds_write2st64_b64 v210, v[46:47], v[0:1] offset1:4
	v_cvt_pk_bf16_f32 v0, v117, v118
	v_cvt_pk_bf16_f32 v1, v2, v3
	v_cvt_pk_bf16_f32 v8, v16, v33
	v_cvt_pk_bf16_f32 v9, v191, v19
	v_cvt_pk_bf16_f32 v2, v34, v20
	v_cvt_pk_bf16_f32 v3, v52, v22
	ds_write2st64_b64 v207, v[0:1], v[8:9] offset0:8 offset1:12
	v_cvt_pk_bf16_f32 v0, v35, v21
	v_cvt_pk_bf16_f32 v1, v53, v23
	v_cvt_pk_bf16_f32 v4, v54, v24
	ds_write2st64_b64 v208, v[2:3], v[0:1] offset0:8 offset1:12
	v_cvt_pk_bf16_f32 v0, v55, v25
	v_cvt_pk_bf16_f32 v1, v57, v27
	v_cvt_pk_bf16_f32 v6, v58, v28
	v_cvt_pk_bf16_f32 v7, v60, v50
	ds_write2st64_b64 v209, v[4:5], v[0:1] offset0:8 offset1:12
	v_cvt_pk_bf16_f32 v0, v59, v29
	v_cvt_pk_bf16_f32 v1, v61, v51
	ds_write2st64_b64 v210, v[6:7], v[0:1] offset0:8 offset1:12
	s_waitcnt lgkmcnt(0)
	ds_read_b64_tr_b16 v[0:1], v151 offset:0
	ds_read_b64_tr_b16 v[2:3], v199 offset:0
	ds_read_b64_tr_b16 v[28:29], v151 offset:1024
	ds_read_b64_tr_b16 v[30:31], v199 offset:1024
	ds_read_b64_tr_b16 v[24:25], v151 offset:2048
	ds_read_b64_tr_b16 v[26:27], v199 offset:2048
	ds_read_b64_tr_b16 v[20:21], v151 offset:3072
	ds_read_b64_tr_b16 v[22:23], v199 offset:3072
	ds_read_b64_tr_b16 v[16:17], v151 offset:4096
	ds_read_b64_tr_b16 v[18:19], v199 offset:4096
	ds_read_b64_tr_b16 v[44:45], v151 offset:5120
	ds_read_b64_tr_b16 v[46:47], v199 offset:5120
	ds_read_b64_tr_b16 v[40:41], v151 offset:6144
	ds_read_b64_tr_b16 v[42:43], v199 offset:6144
	ds_read_b64_tr_b16 v[52:53], v151 offset:7168
	ds_read_b64_tr_b16 v[54:55], v199 offset:7168
	s_waitcnt lgkmcnt(0)
	s_nop 0
	v_mfma_f32_32x32x16_bf16 v[0:15], v[68:71], v[0:3], 0
	v_mfma_f32_32x32x16_bf16 v[0:15], v[64:67], v[28:31], v[0:15]
	v_mfma_f32_32x32x16_bf16 v[24:39], v[76:79], v[24:27], 0
	v_mfma_f32_32x32x16_bf16 v[24:39], v[72:75], v[20:23], v[24:39]
	v_mfma_f32_32x32x16_bf16 v[8:23], v[84:87], v[16:19], 0
	v_mfma_f32_32x32x16_bf16 v[8:23], v[80:83], v[44:47], v[8:23]
	v_mfma_f32_32x32x16_bf16 v[32:47], v[92:95], v[40:43], 0
	v_mfma_f32_32x32x16_bf16 v[32:47], v[88:91], v[52:55], v[32:47]
	s_and_saveexec_b64 s[2:3], s[68:69]
	s_cbranch_execz .LBB0_198
	s_nop 7
	v_add_u32_e32 v16, v200, v146
	v_add_u32_e32 v16, 0x2000, v16
	ds_read2_b64 v[16:19], v16 offset1:2
	v_pk_add_f32 v[6:7], v[6:7], v[30:31]
	v_pk_add_f32 v[2:3], v[2:3], v[26:27]
	v_pk_add_f32 v[14:15], v[14:15], v[38:39]
	v_pk_add_f32 v[10:11], v[10:11], v[34:35]
	v_pk_add_f32 v[6:7], v[6:7], v[14:15]
	v_pk_add_f32 v[2:3], v[2:3], v[10:11]
	s_waitcnt lgkmcnt(0)
	v_lshlrev_b32_e32 v10, 16, v19
	v_and_b32_e32 v11, 0xffff0000, v19
	v_pk_fma_f32 v[6:7], v[102:103], v[10:11], v[6:7]
	v_pk_add_f32 v[0:1], v[0:1], v[24:25]
	v_mul_f32_e32 v10, 0x3d372713, v7
	v_mul_f32_e32 v10, v7, v10
	v_mul_f32_e32 v11, 0x3d372713, v6
	v_fma_f32 v10, v7, v10, v7
	v_mul_f32_e32 v11, v6, v11
	v_mul_f32_e32 v10, 0xbfcc422a, v10
	v_fma_f32 v11, v6, v11, v6
	v_mul_f32_e32 v10, 0x3fb8aa3b, v10
	v_mul_f32_e32 v11, 0xbfcc422a, v11
	v_exp_f32_e32 v10, v10
	v_mul_f32_e32 v11, 0x3fb8aa3b, v11
	v_exp_f32_e32 v11, v11
	v_pk_add_f32 v[8:9], v[8:9], v[32:33]
	v_pk_add_f32 v[4:5], v[4:5], v[28:29]
	v_pk_add_f32 v[12:13], v[12:13], v[36:37]
	v_pk_add_f32 v[0:1], v[0:1], v[8:9]
	v_add_f32_e32 v8, 1.0, v10
	v_pk_add_f32 v[4:5], v[4:5], v[12:13]
	v_rcp_f32_e32 v9, v8
	v_add_f32_e32 v8, 1.0, v11
	v_lshlrev_b32_e32 v10, 16, v18
	v_and_b32_e32 v11, 0xffff0000, v18
	v_pk_fma_f32 v[4:5], v[100:101], v[10:11], v[4:5]
	v_and_b32_e32 v13, 0xffff0000, v17
	v_mul_f32_e32 v10, 0x3d372713, v5
	v_mul_f32_e32 v10, v5, v10
	v_mul_f32_e32 v11, 0x3d372713, v4
	v_fma_f32 v10, v5, v10, v5
	v_mul_f32_e32 v11, v4, v11
	v_mul_f32_e32 v10, 0xbfcc422a, v10
	v_fma_f32 v11, v4, v11, v4
	v_mul_f32_e32 v10, 0x3fb8aa3b, v10
	v_mul_f32_e32 v11, 0xbfcc422a, v11
	v_exp_f32_e32 v10, v10
	v_mul_f32_e32 v11, 0x3fb8aa3b, v11
	v_exp_f32_e32 v12, v11
	v_and_b32_e32 v15, 0xffff0000, v16
	v_add_f32_e32 v10, 1.0, v10
	v_rcp_f32_e32 v11, v10
	v_add_f32_e32 v10, 1.0, v12
	v_lshlrev_b32_e32 v12, 16, v17
	v_pk_fma_f32 v[2:3], v[98:99], v[12:13], v[2:3]
	v_rcp_f32_e32 v8, v8
	v_mul_f32_e32 v12, 0x3d372713, v3
	v_mul_f32_e32 v12, v3, v12
	v_mul_f32_e32 v13, 0x3d372713, v2
	v_fma_f32 v12, v3, v12, v3
	v_mul_f32_e32 v13, v2, v13
	v_mul_f32_e32 v12, 0xbfcc422a, v12
	v_fma_f32 v13, v2, v13, v2
	v_mul_f32_e32 v12, 0x3fb8aa3b, v12
	v_mul_f32_e32 v13, 0xbfcc422a, v13
	v_exp_f32_e32 v12, v12
	v_mul_f32_e32 v13, 0x3fb8aa3b, v13
	v_exp_f32_e32 v14, v13
	s_cmp_eq_u32 s24, -2
	v_add_f32_e32 v12, 1.0, v12
	v_rcp_f32_e32 v13, v12
	v_add_f32_e32 v12, 1.0, v14
	v_lshlrev_b32_e32 v14, 16, v16
	v_pk_fma_f32 v[0:1], v[96:97], v[14:15], v[0:1]
	v_rcp_f32_e32 v12, v12
	v_mul_f32_e32 v14, 0x3d372713, v1
	v_mul_f32_e32 v14, v1, v14
	v_mul_f32_e32 v15, 0x3d372713, v0
	v_fma_f32 v14, v1, v14, v1
	v_mul_f32_e32 v15, v0, v15
	v_mul_f32_e32 v14, 0xbfcc422a, v14
	v_fma_f32 v15, v0, v15, v0
	v_mul_f32_e32 v14, 0x3fb8aa3b, v14
	v_mul_f32_e32 v15, 0xbfcc422a, v15
	v_exp_f32_e32 v14, v14
	v_mul_f32_e32 v15, 0x3fb8aa3b, v15
	v_exp_f32_e32 v16, v15
	v_rcp_f32_e32 v10, v10
	v_add_f32_e32 v14, 1.0, v14
	v_rcp_f32_e32 v15, v14
	v_add_f32_e32 v14, 1.0, v16
	v_rcp_f32_e32 v14, v14
	s_cselect_b64 vcc, -1, 0
	s_ashr_i32 s53, s52, 31
	v_pk_mul_f32 v[6:7], v[6:7], v[8:9]
	v_lshl_add_u64 v[8:9], s[52:53], 4, v[120:121]
	v_cndmask_b32_e64 v9, v9, 0, vcc
	v_cndmask_b32_e32 v8, v8, v154, vcc
	v_pk_mul_f32 v[2:3], v[2:3], v[12:13]
	v_pk_mul_f32 v[0:1], v[0:1], v[14:15]
	v_lshlrev_b64 v[8:9], 11, v[8:9]
	v_pk_mul_f32 v[4:5], v[4:5], v[10:11]
	v_lshl_add_u64 v[8:9], v[126:127], 0, v[8:9]
	v_cvt_pk_bf16_f32 v0, v0, v1
	v_cvt_pk_bf16_f32 v1, v2, v3
	v_cvt_pk_bf16_f32 v2, v4, v5
	v_cvt_pk_bf16_f32 v3, v6, v7
	global_store_dwordx2 v[8:9], v[0:1], off
	global_store_dwordx2 v[8:9], v[2:3], off offset:16

.LBB0_199:
	s_waitcnt vmcnt(9)
	v_mfma_f32_32x32x16_bf16 v[16:31], v[112:115], v[132:135], 0
	v_mov_b32_e32 v32, v49
	v_mov_b32_e32 v33, v51
	v_mul_f32_e64 v32, v174, v32
	v_mul_f32_e64 v33, v175, v33
	ds_write_b128 v148, v[112:115] offset:8192
	v_sub_f32_e32 v32, v32, v33
	v_mov_b32_e32 v33, v49
	s_cmp_gt_i32 s24, -3
	s_nop 3
	v_add_f32_e32 v148, v32, v16
	v_mov_b32_e32 v32, v51
	v_pk_mul_f32 v[50:51], v[176:177], v[50:51] op_sel_hi:[1,0]
	v_pk_mul_f32 v[52:53], v[174:175], v[32:33]
	v_pk_fma_f32 v[186:187], v[172:173], v[48:49], v[50:51] neg_lo:[0,0,1] neg_hi:[0,0,1]
	v_pk_fma_f32 v[48:49], v[172:173], v[48:49], v[50:51] op_sel_hi:[1,0,1]
	v_mfma_f32_32x32x16_bf16 v[0:15], v[112:115], v[128:131], 0
	v_add_f32_e32 v16, v52, v53
	v_mov_b32_e32 v187, v49
	s_cselect_b64 s[2:3], -1, 0
	s_or_b64 s[52:53], s[2:3], s[50:51]
	v_mfma_f32_32x32x16_bf16 v[48:63], v[112:115], v[136:139], 0
	s_nop 6
	v_mov_b32_e32 v188, v0
	v_mfma_f32_32x32x16_bf16 v[32:47], v[112:115], v[140:143], 0
	s_nop 2
	v_mov_b32_e32 v189, v48
	v_add_f32_e64 v112, v186, v188
	v_add_f32_e64 v113, v187, v189
	v_mul_f32_e64 v114, v172, v112
	v_mul_f32_e64 v115, v173, v113
	v_sub_f32_e32 v0, v114, v115
	v_pk_mul_f32 v[114:115], v[176:177], v[112:113]
	s_nop 1
	v_add_f32_e32 v16, v16, v32
	v_add_f32_e32 v0, v1, v0
	v_add_f32_e32 v1, v114, v115
	v_add_f32_e32 v114, v49, v1
	v_pk_mul_f32 v[48:49], v[178:179], v[16:17] op_sel_hi:[1,0]
	v_mov_b32_e32 v32, v17
	v_pk_fma_f32 v[186:187], v[174:175], v[148:149], v[48:49] neg_lo:[0,0,1] neg_hi:[0,0,1]
	v_pk_fma_f32 v[48:49], v[174:175], v[148:149], v[48:49] op_sel_hi:[1,0,1]
	s_nop 0
	v_mov_b32_e32 v187, v49
	v_pk_add_f32 v[32:33], v[32:33], v[186:187]
	s_nop 0
	v_pk_mul_f32 v[48:49], v[174:175], v[32:33]
	s_nop 0
	v_sub_f32_e32 v1, v48, v49
	v_pk_mul_f32 v[48:49], v[178:179], v[32:33]
	v_add_f32_e32 v187, v18, v1
	v_add_f32_e32 v1, v48, v49
	v_pk_mul_f32 v[48:49], v[176:177], v[114:115] op_sel_hi:[1,0]
	v_add_f32_e32 v189, v34, v1
	v_pk_fma_f32 v[190:191], v[172:173], v[0:1], v[48:49] neg_lo:[0,0,1] neg_hi:[0,0,1]
	v_pk_fma_f32 v[48:49], v[172:173], v[0:1], v[48:49] op_sel_hi:[1,0,1]
	v_mul_f32_e32 v193, v174, v187
	v_mov_b32_e32 v191, v49
	v_mov_b32_e32 v48, v2
	v_mov_b32_e32 v49, v50
	v_pk_add_f32 v[190:191], v[48:49], v[190:191]
	v_mul_f32_e32 v213, v175, v189
	v_pk_mul_f32 v[48:49], v[172:173], v[190:191]
	v_mov_b32_e32 v18, v3
	v_mov_b32_e32 v192, v48
	v_mov_b32_e32 v212, v49
	v_pk_add_f32 v[48:49], v[192:193], v[212:213] neg_lo:[0,1] neg_hi:[0,1]
	v_mov_b32_e32 v188, v191
	v_pk_add_f32 v[2:3], v[18:19], v[48:49]
	v_pk_mul_f32 v[18:19], v[180:181], v[188:189]
	v_mov_b32_e32 v186, v190
	v_pk_fma_f32 v[18:19], v[182:183], v[186:187], v[18:19]
	v_mov_b32_e32 v34, v51
	v_pk_add_f32 v[18:19], v[34:35], v[18:19]
	v_mov_b32_e32 v48, v4
	v_pk_mul_f32 v[34:35], v[182:183], v[18:19]
	v_mov_b32_e32 v49, v20
	v_pk_fma_f32 v[34:35], v[180:181], v[2:3], v[34:35] neg_lo:[0,0,1] neg_hi:[0,0,1]
	v_mov_b32_e32 v50, v52
	v_pk_add_f32 v[34:35], v[48:49], v[34:35]
	v_pk_mul_f32 v[48:49], v[180:181], v[18:19]
	v_mov_b32_e32 v51, v36
	v_pk_fma_f32 v[48:49], v[182:183], v[2:3], v[48:49]
	v_mov_b32_e32 v20, v5
	v_pk_add_f32 v[192:193], v[50:51], v[48:49]
	v_mov_b32_e32 v36, v53
	v_pk_mul_f32 v[48:49], v[182:183], v[192:193]
	v_mov_b32_e32 v50, v54
	v_pk_fma_f32 v[48:49], v[180:181], v[34:35], v[48:49] neg_lo:[0,0,1] neg_hi:[0,0,1]
	v_mov_b32_e32 v51, v38
	v_pk_add_f32 v[4:5], v[20:21], v[48:49]
	v_pk_mul_f32 v[20:21], v[180:181], v[192:193]
	v_mov_b32_e32 v48, v6
	v_pk_fma_f32 v[20:21], v[182:183], v[34:35], v[20:21]
	v_mov_b32_e32 v49, v22
	v_pk_add_f32 v[20:21], v[36:37], v[20:21]
	v_mov_b32_e32 v22, v7
	v_pk_mul_f32 v[36:37], v[182:183], v[20:21]
	v_mov_b32_e32 v38, v55
	v_pk_fma_f32 v[36:37], v[180:181], v[4:5], v[36:37] neg_lo:[0,0,1] neg_hi:[0,0,1]
	v_cvt_pk_bf16_f32 v0, v112, v0
	v_pk_add_f32 v[36:37], v[48:49], v[36:37]
	v_pk_mul_f32 v[48:49], v[180:181], v[20:21]
	v_cvt_pk_bf16_f32 v1, v190, v2
	v_pk_fma_f32 v[48:49], v[182:183], v[4:5], v[48:49]
	v_cvt_pk_bf16_f32 v2, v148, v32
	v_pk_add_f32 v[52:53], v[50:51], v[48:49]
	v_mov_b32_e32 v50, v8
	v_pk_mul_f32 v[48:49], v[182:183], v[52:53]
	v_mov_b32_e32 v51, v24
	v_pk_fma_f32 v[48:49], v[180:181], v[36:37], v[48:49] neg_lo:[0,0,1] neg_hi:[0,0,1]
	v_mov_b32_e32 v24, v9
	v_pk_add_f32 v[6:7], v[22:23], v[48:49]
	v_pk_mul_f32 v[22:23], v[180:181], v[52:53]
	v_cvt_pk_bf16_f32 v3, v187, v3
	v_pk_fma_f32 v[22:23], v[182:183], v[36:37], v[22:23]
	ds_write2st64_b64 v207, v[0:1], v[2:3] offset1:4
	v_pk_add_f32 v[22:23], v[38:39], v[22:23]
	v_cvt_pk_bf16_f32 v0, v35, v5
	v_pk_mul_f32 v[38:39], v[182:183], v[22:23]
	v_pk_mul_f32 v[48:49], v[180:181], v[22:23]
	v_pk_fma_f32 v[38:39], v[180:181], v[6:7], v[38:39] neg_lo:[0,0,1] neg_hi:[0,0,1]
	v_pk_fma_f32 v[48:49], v[182:183], v[6:7], v[48:49]
	v_pk_add_f32 v[38:39], v[50:51], v[38:39]
	v_mov_b32_e32 v50, v56
	v_mov_b32_e32 v51, v40
	v_pk_add_f32 v[54:55], v[50:51], v[48:49]
	v_mov_b32_e32 v40, v57
	v_pk_mul_f32 v[48:49], v[182:183], v[54:55]
	v_mov_b32_e32 v50, v58
	v_pk_fma_f32 v[48:49], v[180:181], v[38:39], v[48:49] neg_lo:[0,0,1] neg_hi:[0,0,1]
	v_mov_b32_e32 v51, v42
	v_pk_add_f32 v[8:9], v[24:25], v[48:49]
	v_pk_mul_f32 v[24:25], v[180:181], v[54:55]
	v_mov_b32_e32 v48, v10
	v_pk_fma_f32 v[24:25], v[182:183], v[38:39], v[24:25]
	v_mov_b32_e32 v49, v26
	v_pk_add_f32 v[24:25], v[40:41], v[24:25]
	v_mov_b32_e32 v42, v59
	v_pk_mul_f32 v[40:41], v[182:183], v[24:25]
	v_mov_b32_e32 v26, v11
	v_pk_fma_f32 v[40:41], v[180:181], v[8:9], v[40:41] neg_lo:[0,0,1] neg_hi:[0,0,1]
	v_cvt_pk_bf16_f32 v1, v37, v7
	v_pk_add_f32 v[40:41], v[48:49], v[40:41]
	v_pk_mul_f32 v[48:49], v[180:181], v[24:25]
	v_pk_mov_b32 v[2:3], v[190:191], v[18:19] op_sel:[1,0]
	v_pk_fma_f32 v[48:49], v[182:183], v[8:9], v[48:49]
	s_nop 0
	v_pk_add_f32 v[56:57], v[50:51], v[48:49]
	s_nop 0
	v_pk_mul_f32 v[48:49], v[180:181], v[56:57]
	v_pk_mul_f32 v[58:59], v[182:183], v[56:57]
	v_pk_fma_f32 v[48:49], v[182:183], v[40:41], v[48:49]
	v_pk_fma_f32 v[58:59], v[180:181], v[40:41], v[58:59] neg_lo:[0,0,1] neg_hi:[0,0,1]
	v_pk_add_f32 v[42:43], v[42:43], v[48:49]
	v_pk_add_f32 v[10:11], v[26:27], v[58:59]
	v_pk_mul_f32 v[48:49], v[182:183], v[42:43]
	v_pk_mul_f32 v[50:51], v[180:181], v[42:43]
	v_pk_fma_f32 v[26:27], v[180:181], v[10:11], v[48:49] neg_lo:[0,0,1] neg_hi:[0,0,1]
	v_mov_b32_e32 v48, v12
	v_mov_b32_e32 v49, v28
	v_pk_add_f32 v[26:27], v[48:49], v[26:27]
	v_pk_fma_f32 v[48:49], v[182:183], v[10:11], v[50:51]
	v_mov_b32_e32 v50, v60
	v_mov_b32_e32 v51, v44
	v_pk_add_f32 v[58:59], v[50:51], v[48:49]
	v_mov_b32_e32 v28, v13
	v_pk_mul_f32 v[48:49], v[182:183], v[58:59]
	v_mov_b32_e32 v44, v61
	v_pk_fma_f32 v[48:49], v[180:181], v[26:27], v[48:49] neg_lo:[0,0,1] neg_hi:[0,0,1]
	v_mov_b32_e32 v50, v62
	v_pk_add_f32 v[12:13], v[28:29], v[48:49]
	v_pk_mul_f32 v[28:29], v[180:181], v[58:59]
	v_mov_b32_e32 v48, v14
	v_pk_fma_f32 v[28:29], v[182:183], v[26:27], v[28:29]
	v_mov_b32_e32 v49, v30
	v_pk_add_f32 v[28:29], v[44:45], v[28:29]
	v_mov_b32_e32 v51, v46
	v_pk_mul_f32 v[44:45], v[182:183], v[28:29]
	v_mov_b32_e32 v30, v15
	v_pk_fma_f32 v[44:45], v[180:181], v[12:13], v[44:45] neg_lo:[0,0,1] neg_hi:[0,0,1]
	v_mov_b32_e32 v46, v63
	v_pk_add_f32 v[44:45], v[48:49], v[44:45]
	v_pk_mul_f32 v[48:49], v[180:181], v[28:29]
	v_cvt_pk_bf16_f32 v5, v56, v42
	v_pk_fma_f32 v[48:49], v[182:183], v[12:13], v[48:49]
	s_nop 0
	v_pk_add_f32 v[60:61], v[50:51], v[48:49]
	s_nop 0
	v_pk_mul_f32 v[14:15], v[180:181], v[60:61]
	v_pk_mul_f32 v[48:49], v[182:183], v[60:61]
	v_pk_fma_f32 v[14:15], v[182:183], v[44:45], v[14:15]
	v_pk_fma_f32 v[48:49], v[180:181], v[44:45], v[48:49] neg_lo:[0,0,1] neg_hi:[0,0,1]
	v_pk_add_f32 v[50:51], v[46:47], v[14:15]
	v_cvt_pk_bf16_f32 v14, v34, v4
	v_cvt_pk_bf16_f32 v15, v36, v6
	v_pk_add_f32 v[48:49], v[30:31], v[48:49]
	v_cvt_pk_bf16_f32 v30, v38, v8
	v_cvt_pk_bf16_f32 v31, v40, v10
	ds_write2st64_b64 v208, v[14:15], v[0:1] offset1:4
	v_cvt_pk_bf16_f32 v0, v39, v9
	v_cvt_pk_bf16_f32 v1, v41, v11
	v_cvt_pk_bf16_f32 v46, v26, v12
	v_cvt_pk_bf16_f32 v47, v44, v48
	ds_write2st64_b64 v209, v[30:31], v[0:1] offset1:4
	v_cvt_pk_bf16_f32 v0, v27, v13
	v_cvt_pk_bf16_f32 v1, v45, v49
	ds_write2st64_b64 v210, v[46:47], v[0:1] offset1:4
	v_cvt_pk_bf16_f32 v0, v113, v114
	v_cvt_pk_bf16_f32 v1, v2, v3
	v_cvt_pk_bf16_f32 v8, v16, v33
	v_cvt_pk_bf16_f32 v9, v189, v19
	v_cvt_pk_bf16_f32 v2, v192, v20
	v_cvt_pk_bf16_f32 v3, v52, v22
	ds_write2st64_b64 v207, v[0:1], v[8:9] offset0:8 offset1:12
	v_cvt_pk_bf16_f32 v0, v193, v21
	v_cvt_pk_bf16_f32 v1, v53, v23
	v_cvt_pk_bf16_f32 v4, v54, v24
	ds_write2st64_b64 v208, v[2:3], v[0:1] offset0:8 offset1:12
	v_cvt_pk_bf16_f32 v0, v55, v25
	v_cvt_pk_bf16_f32 v1, v57, v43
	v_cvt_pk_bf16_f32 v6, v58, v28
	v_cvt_pk_bf16_f32 v7, v60, v50
	ds_write2st64_b64 v209, v[4:5], v[0:1] offset0:8 offset1:12
	v_cvt_pk_bf16_f32 v0, v59, v29
	v_cvt_pk_bf16_f32 v1, v61, v51
	ds_write2st64_b64 v210, v[6:7], v[0:1] offset0:8 offset1:12
	s_waitcnt lgkmcnt(0)
	ds_read_b64_tr_b16 v[0:1], v151 offset:0
	ds_read_b64_tr_b16 v[2:3], v199 offset:0
	ds_read_b64_tr_b16 v[28:29], v151 offset:1024
	ds_read_b64_tr_b16 v[30:31], v199 offset:1024
	ds_read_b64_tr_b16 v[24:25], v151 offset:2048
	ds_read_b64_tr_b16 v[26:27], v199 offset:2048
	ds_read_b64_tr_b16 v[20:21], v151 offset:3072
	ds_read_b64_tr_b16 v[22:23], v199 offset:3072
	ds_read_b64_tr_b16 v[16:17], v151 offset:4096
	ds_read_b64_tr_b16 v[18:19], v199 offset:4096
	ds_read_b64_tr_b16 v[44:45], v151 offset:5120
	ds_read_b64_tr_b16 v[46:47], v199 offset:5120
	ds_read_b64_tr_b16 v[40:41], v151 offset:6144
	ds_read_b64_tr_b16 v[42:43], v199 offset:6144
	ds_read_b64_tr_b16 v[52:53], v151 offset:7168
	ds_read_b64_tr_b16 v[54:55], v199 offset:7168
	s_waitcnt lgkmcnt(0)
	s_nop 0
	v_mfma_f32_32x32x16_bf16 v[0:15], v[68:71], v[0:3], 0
	v_mfma_f32_32x32x16_bf16 v[0:15], v[64:67], v[28:31], v[0:15]
	v_mfma_f32_32x32x16_bf16 v[24:39], v[76:79], v[24:27], 0
	v_mfma_f32_32x32x16_bf16 v[24:39], v[72:75], v[20:23], v[24:39]
	v_mfma_f32_32x32x16_bf16 v[8:23], v[84:87], v[16:19], 0
	v_mfma_f32_32x32x16_bf16 v[8:23], v[80:83], v[44:47], v[8:23]
	v_mfma_f32_32x32x16_bf16 v[32:47], v[92:95], v[40:43], 0
	v_mfma_f32_32x32x16_bf16 v[32:47], v[88:91], v[52:55], v[32:47]
	s_and_saveexec_b64 s[2:3], s[52:53]
	s_cbranch_execz .LBB0_186
	s_nop 7
	v_add_u32_e32 v16, v200, v146
	v_add_u32_e32 v16, 0x2000, v16
	ds_read2_b64 v[16:19], v16 offset1:2
	v_pk_add_f32 v[6:7], v[6:7], v[30:31]
	v_pk_add_f32 v[2:3], v[2:3], v[26:27]
	v_pk_add_f32 v[14:15], v[14:15], v[38:39]
	v_pk_add_f32 v[10:11], v[10:11], v[34:35]
	v_pk_add_f32 v[6:7], v[6:7], v[14:15]
	v_pk_add_f32 v[2:3], v[2:3], v[10:11]
	s_waitcnt lgkmcnt(0)
	v_lshlrev_b32_e32 v10, 16, v19
	v_and_b32_e32 v11, 0xffff0000, v19
	v_pk_fma_f32 v[6:7], v[102:103], v[10:11], v[6:7]
	v_pk_add_f32 v[0:1], v[0:1], v[24:25]
	v_mul_f32_e32 v10, 0x3d372713, v7
	v_mul_f32_e32 v10, v7, v10
	v_mul_f32_e32 v11, 0x3d372713, v6
	v_fma_f32 v10, v7, v10, v7
	v_mul_f32_e32 v11, v6, v11
	v_mul_f32_e32 v10, 0xbfcc422a, v10
	v_fma_f32 v11, v6, v11, v6
	v_mul_f32_e32 v10, 0x3fb8aa3b, v10
	v_mul_f32_e32 v11, 0xbfcc422a, v11
	v_exp_f32_e32 v10, v10
	v_mul_f32_e32 v11, 0x3fb8aa3b, v11
	v_exp_f32_e32 v11, v11
	v_pk_add_f32 v[8:9], v[8:9], v[32:33]
	v_pk_add_f32 v[4:5], v[4:5], v[28:29]
	v_pk_add_f32 v[12:13], v[12:13], v[36:37]
	v_pk_add_f32 v[0:1], v[0:1], v[8:9]
	v_add_f32_e32 v8, 1.0, v10
	v_pk_add_f32 v[4:5], v[4:5], v[12:13]
	v_rcp_f32_e32 v9, v8
	v_add_f32_e32 v8, 1.0, v11
	v_lshlrev_b32_e32 v10, 16, v18
	v_and_b32_e32 v11, 0xffff0000, v18
	v_pk_fma_f32 v[4:5], v[100:101], v[10:11], v[4:5]
	v_and_b32_e32 v13, 0xffff0000, v17
	v_mul_f32_e32 v10, 0x3d372713, v5
	v_mul_f32_e32 v10, v5, v10
	v_mul_f32_e32 v11, 0x3d372713, v4
	v_fma_f32 v10, v5, v10, v5
	v_mul_f32_e32 v11, v4, v11
	v_mul_f32_e32 v10, 0xbfcc422a, v10
	v_fma_f32 v11, v4, v11, v4
	v_mul_f32_e32 v10, 0x3fb8aa3b, v10
	v_mul_f32_e32 v11, 0xbfcc422a, v11
	v_exp_f32_e32 v10, v10
	v_mul_f32_e32 v11, 0x3fb8aa3b, v11
	v_exp_f32_e32 v12, v11
	v_and_b32_e32 v15, 0xffff0000, v16
	v_add_f32_e32 v10, 1.0, v10
	v_rcp_f32_e32 v11, v10
	v_add_f32_e32 v10, 1.0, v12
	v_lshlrev_b32_e32 v12, 16, v17
	v_pk_fma_f32 v[2:3], v[98:99], v[12:13], v[2:3]
	v_rcp_f32_e32 v8, v8
	v_mul_f32_e32 v12, 0x3d372713, v3
	v_mul_f32_e32 v12, v3, v12
	v_mul_f32_e32 v13, 0x3d372713, v2
	v_fma_f32 v12, v3, v12, v3
	v_mul_f32_e32 v13, v2, v13
	v_mul_f32_e32 v12, 0xbfcc422a, v12
	v_fma_f32 v13, v2, v13, v2
	v_mul_f32_e32 v12, 0x3fb8aa3b, v12
	v_mul_f32_e32 v13, 0xbfcc422a, v13
	v_exp_f32_e32 v12, v12
	v_mul_f32_e32 v13, 0x3fb8aa3b, v13
	v_exp_f32_e32 v14, v13
	s_cmp_eq_u32 s24, -3
	v_add_f32_e32 v12, 1.0, v12
	v_rcp_f32_e32 v13, v12
	v_add_f32_e32 v12, 1.0, v14
	v_lshlrev_b32_e32 v14, 16, v16
	v_pk_fma_f32 v[0:1], v[96:97], v[14:15], v[0:1]
	v_rcp_f32_e32 v12, v12
	v_mul_f32_e32 v14, 0x3d372713, v1
	v_mul_f32_e32 v14, v1, v14
	v_mul_f32_e32 v15, 0x3d372713, v0
	v_fma_f32 v14, v1, v14, v1
	v_mul_f32_e32 v15, v0, v15
	v_mul_f32_e32 v14, 0xbfcc422a, v14
	v_fma_f32 v15, v0, v15, v0
	v_mul_f32_e32 v14, 0x3fb8aa3b, v14
	v_mul_f32_e32 v15, 0xbfcc422a, v15
	v_exp_f32_e32 v14, v14
	v_mul_f32_e32 v15, 0x3fb8aa3b, v15
	v_exp_f32_e32 v16, v15
	v_rcp_f32_e32 v10, v10
	v_add_f32_e32 v14, 1.0, v14
	v_rcp_f32_e32 v15, v14
	v_add_f32_e32 v14, 1.0, v16
	v_rcp_f32_e32 v14, v14
	s_cselect_b64 vcc, -1, 0
	s_ashr_i32 s15, s14, 31
	v_pk_mul_f32 v[6:7], v[6:7], v[8:9]
	v_lshl_add_u64 v[8:9], s[14:15], 4, v[120:121]
	v_cndmask_b32_e64 v9, v9, 0, vcc
	v_cndmask_b32_e32 v8, v8, v154, vcc
	v_pk_mul_f32 v[2:3], v[2:3], v[12:13]
	v_pk_mul_f32 v[0:1], v[0:1], v[14:15]
	v_lshlrev_b64 v[8:9], 11, v[8:9]
	v_pk_mul_f32 v[4:5], v[4:5], v[10:11]
	v_lshl_add_u64 v[8:9], v[126:127], 0, v[8:9]
	v_cvt_pk_bf16_f32 v0, v0, v1
	v_cvt_pk_bf16_f32 v1, v2, v3
	v_cvt_pk_bf16_f32 v2, v4, v5
	v_cvt_pk_bf16_f32 v3, v6, v7
	global_store_dwordx2 v[8:9], v[0:1], off
	global_store_dwordx2 v[8:9], v[2:3], off offset:16
	s_branch .LBB0_186
